# attention loops: cross-half row-max exchange via v_permlane32_swap instead of ds_bpermute LDS round trip (band loop, MLA loop, MLA diagonal tile)
# speedup vs baseline: 1.0003x; 1.0001x over previous
.LBB0_459:
	s_nop 0
	v_max_f32_e32 v2, v147, v147
	s_nop 2
	v_max_f32_e32 v50, v146, v146
	v_max_f32_e32 v2, v50, v2
	v_max3_f32 v2, v2, v144, v145
	v_max3_f32 v2, v2, v142, v143
	v_max3_f32 v2, v2, v140, v141
	v_max3_f32 v2, v2, v138, v139
	v_max3_f32 v2, v2, v134, v135
	v_max3_f32 v2, v2, v130, v131
	v_max3_f32 v2, v2, v16, v17
	v_max3_f32 v2, v2, v136, v137
	v_max3_f32 v2, v2, v132, v133
	v_max3_f32 v2, v2, v14, v15
	v_max3_f32 v2, v2, v12, v13
	v_max3_f32 v2, v2, v10, v11
	v_max3_f32 v2, v2, v8, v9
	v_max3_f32 v2, v2, v6, v7
	v_max3_f32 v2, v2, v4, v5
	v_mov_b32_e32 v50, v2
	s_nop 1
	v_permlane32_swap_b32_e32 v50, v2
	s_waitcnt lgkmcnt(0)
	v_max3_f32 v50, v173, v2, v50
	v_sub_f32_e32 v2, v173, v50
	v_exp_f32_e32 v2, v2
	s_nop 0
	v_cmp_neq_f32_e32 vcc, 1.0, v2
	s_cbranch_vccz .LBB0_461
	v_pk_mul_f32 v[48:49], v[48:49], v[2:3] op_sel_hi:[1,0]
	v_pk_mul_f32 v[46:47], v[46:47], v[2:3] op_sel_hi:[1,0]
	v_pk_mul_f32 v[44:45], v[44:45], v[2:3] op_sel_hi:[1,0]
	v_pk_mul_f32 v[42:43], v[42:43], v[2:3] op_sel_hi:[1,0]
	v_pk_mul_f32 v[40:41], v[40:41], v[2:3] op_sel_hi:[1,0]
	v_pk_mul_f32 v[38:39], v[38:39], v[2:3] op_sel_hi:[1,0]
	v_pk_mul_f32 v[36:37], v[36:37], v[2:3] op_sel_hi:[1,0]
	v_pk_mul_f32 v[34:35], v[34:35], v[2:3] op_sel_hi:[1,0]
	v_pk_mul_f32 v[32:33], v[32:33], v[2:3] op_sel_hi:[1,0]
	v_pk_mul_f32 v[30:31], v[30:31], v[2:3] op_sel_hi:[1,0]
	v_pk_mul_f32 v[28:29], v[28:29], v[2:3] op_sel_hi:[1,0]
	v_pk_mul_f32 v[26:27], v[26:27], v[2:3] op_sel_hi:[1,0]
	v_pk_mul_f32 v[24:25], v[24:25], v[2:3] op_sel_hi:[1,0]
	v_pk_mul_f32 v[22:23], v[22:23], v[2:3] op_sel_hi:[1,0]
	v_pk_mul_f32 v[20:21], v[20:21], v[2:3] op_sel_hi:[1,0]
	v_pk_mul_f32 v[18:19], v[18:19], v[2:3] op_sel_hi:[1,0]

.LBB0_1611:
	v_lshl_add_u64 v[66:67], v[214:215], 0, s[56:57]
	v_cndmask_b32_e64 v67, v217, v67, s[4:5]
	v_cndmask_b32_e64 v66, v216, v66, s[4:5]
	s_waitcnt vmcnt(63) expcnt(7) lgkmcnt(15)
	s_barrier
	s_waitcnt vmcnt(4)
	ds_write_b128 v229, v[146:149]
	s_waitcnt vmcnt(3)
	ds_write_b128 v230, v[150:153]
	s_waitcnt vmcnt(2)
	ds_write_b128 v231, v[154:157]
	s_waitcnt vmcnt(1)
	ds_write_b128 v232, v[162:165] offset:25600
	s_waitcnt vmcnt(0)
	ds_write_b128 v233, v[158:161] offset:25600
	s_waitcnt lgkmcnt(0)
	s_barrier
	global_load_dwordx4 v[146:149], v[66:67], off
	v_lshl_add_u64 v[66:67], v[210:211], 0, s[56:57]
	v_cndmask_b32_e64 v67, v213, v67, s[8:9]
	v_cndmask_b32_e64 v66, v212, v66, s[8:9]
	global_load_dwordx4 v[150:153], v[66:67], off
	v_lshl_add_u64 v[66:67], v[206:207], 0, s[56:57]
	v_cndmask_b32_e64 v67, v209, v67, s[12:13]
	v_cndmask_b32_e64 v66, v208, v66, s[12:13]
	global_load_dwordx4 v[154:157], v[66:67], off
	v_lshl_add_u64 v[66:67], v[204:205], 0, s[56:57]
	v_lshl_add_u64 v[68:69], v[202:203], 0, s[56:57]
	global_load_dwordx4 v[162:165], v[66:67], off
	global_load_dwordx4 v[158:161], v[68:69], off
	s_cmp_gt_i32 s58, s29
	s_cbranch_scc1 .LBB0_1615
	v_add_u32_e32 v235, v226, v225
	ds_read_b128 v[66:69], v235
	ds_read_b128 v[236:239], v235 offset:32
	ds_read_b128 v[70:73], v235 offset:12800
	ds_read_b128 v[244:247], v235 offset:12832
	s_waitcnt lgkmcnt(3)
	v_mfma_f32_32x32x16_bf16 v[82:97], v[66:69], v[142:145], 0
	ds_read_b128 v[248:251], v235 offset:64
	ds_read_b128 v[252:255], v235 offset:12864
	s_waitcnt lgkmcnt(3)
	v_mfma_f32_32x32x16_bf16 v[66:81], v[70:73], v[142:145], 0
	v_mfma_f32_32x32x16_bf16 v[82:97], v[236:239], v[138:141], v[82:97]
	s_waitcnt lgkmcnt(2)
	v_mfma_f32_32x32x16_bf16 v[66:81], v[244:247], v[138:141], v[66:81]
	ds_read_b128 v[236:239], v235 offset:96
	ds_read_b128 v[244:247], v235 offset:12896
	s_waitcnt lgkmcnt(3)
	v_mfma_f32_32x32x16_bf16 v[82:97], v[248:251], v[134:137], v[82:97]
	s_waitcnt lgkmcnt(2)
	v_mfma_f32_32x32x16_bf16 v[66:81], v[252:255], v[134:137], v[66:81]
	ds_read_b128 v[248:251], v235 offset:128
	ds_read_b128 v[252:255], v235 offset:12928
	s_waitcnt lgkmcnt(3)
	v_mfma_f32_32x32x16_bf16 v[82:97], v[236:239], v[130:133], v[82:97]
	s_waitcnt lgkmcnt(2)
	v_mfma_f32_32x32x16_bf16 v[66:81], v[244:247], v[130:133], v[66:81]
	ds_read_b128 v[236:239], v235 offset:160
	ds_read_b128 v[244:247], v235 offset:12960
	s_waitcnt lgkmcnt(3)
	v_mfma_f32_32x32x16_bf16 v[82:97], v[248:251], v[126:129], v[82:97]
	s_waitcnt lgkmcnt(2)
	v_mfma_f32_32x32x16_bf16 v[66:81], v[252:255], v[126:129], v[66:81]
	ds_read_b128 v[248:251], v235 offset:192
	ds_read_b128 v[252:255], v235 offset:12992
	s_waitcnt lgkmcnt(3)
	v_mfma_f32_32x32x16_bf16 v[82:97], v[236:239], v[122:125], v[82:97]
	s_waitcnt lgkmcnt(2)
	v_mfma_f32_32x32x16_bf16 v[66:81], v[244:247], v[122:125], v[66:81]
	ds_read_b128 v[236:239], v235 offset:224
	ds_read_b128 v[244:247], v235 offset:13024
	s_waitcnt lgkmcnt(3)
	v_mfma_f32_32x32x16_bf16 v[82:97], v[248:251], v[118:121], v[82:97]
	s_waitcnt lgkmcnt(2)
	v_mfma_f32_32x32x16_bf16 v[66:81], v[252:255], v[118:121], v[66:81]
	ds_read_b128 v[248:251], v235 offset:256
	ds_read_b128 v[252:255], v235 offset:13056
	s_waitcnt lgkmcnt(3)
	v_mfma_f32_32x32x16_bf16 v[82:97], v[236:239], v[114:117], v[82:97]
	s_waitcnt lgkmcnt(2)
	v_mfma_f32_32x32x16_bf16 v[66:81], v[244:247], v[114:117], v[66:81]
	ds_read_b128 v[236:239], v235 offset:288
	ds_read_b128 v[244:247], v235 offset:13088
	s_waitcnt lgkmcnt(3)
	v_mfma_f32_32x32x16_bf16 v[82:97], v[248:251], v[110:113], v[82:97]
	s_waitcnt lgkmcnt(2)
	v_mfma_f32_32x32x16_bf16 v[66:81], v[252:255], v[110:113], v[66:81]
	ds_read_b128 v[248:251], v235 offset:320
	ds_read_b128 v[252:255], v235 offset:13120
	s_waitcnt lgkmcnt(3)
	v_mfma_f32_32x32x16_bf16 v[82:97], v[236:239], v[106:109], v[82:97]
	s_waitcnt lgkmcnt(2)
	v_mfma_f32_32x32x16_bf16 v[66:81], v[244:247], v[106:109], v[66:81]
	ds_read_b128 v[236:239], v235 offset:352
	ds_read_b128 v[244:247], v235 offset:13152
	s_waitcnt lgkmcnt(3)
	v_mfma_f32_32x32x16_bf16 v[82:97], v[248:251], v[102:105], v[82:97]
	s_waitcnt lgkmcnt(2)
	v_mfma_f32_32x32x16_bf16 v[66:81], v[252:255], v[102:105], v[66:81]
	s_waitcnt lgkmcnt(1)
	v_mfma_f32_32x32x16_bf16 v[82:97], v[236:239], v[98:101], v[82:97]
	s_waitcnt lgkmcnt(0)
	v_mfma_f32_32x32x16_bf16 v[66:81], v[244:247], v[98:101], v[66:81]
	s_nop 9
	v_max_f32_e32 v235, v83, v83
	v_max_f32_e32 v236, v82, v82
	v_max_f32_e32 v235, v236, v235
	v_max3_f32 v235, v235, v84, v85
	v_max3_f32 v235, v235, v86, v87
	v_max3_f32 v235, v235, v88, v89
	v_max3_f32 v235, v235, v90, v91
	v_max3_f32 v235, v235, v92, v93
	v_max3_f32 v235, v235, v94, v95
	v_max3_f32 v235, v235, v96, v97
	v_max3_f32 v235, v235, v66, v67
	v_max3_f32 v235, v235, v68, v69
	v_max3_f32 v235, v235, v70, v71
	v_max3_f32 v235, v235, v72, v73
	v_max3_f32 v235, v235, v74, v75
	v_max3_f32 v235, v235, v76, v77
	v_max3_f32 v235, v235, v78, v79
	v_max3_f32 v235, v235, v80, v81
	v_mov_b32_e32 v236, v235
	s_nop 1
	v_permlane32_swap_b32_e32 v236, v235
	s_waitcnt lgkmcnt(0)
	v_max3_f32 v235, v218, v235, v236
	v_sub_f32_e32 v218, v218, v235
	v_exp_f32_e32 v218, v218
	s_nop 0
	v_cmp_neq_f32_e32 vcc, 1.0, v218
	s_cbranch_vccz .LBB0_1614
	v_pk_mul_f32 v[64:65], v[64:65], v[218:219] op_sel_hi:[1,0]
	v_pk_mul_f32 v[62:63], v[62:63], v[218:219] op_sel_hi:[1,0]
	v_pk_mul_f32 v[60:61], v[60:61], v[218:219] op_sel_hi:[1,0]
	v_pk_mul_f32 v[58:59], v[58:59], v[218:219] op_sel_hi:[1,0]
	v_pk_mul_f32 v[56:57], v[56:57], v[218:219] op_sel_hi:[1,0]
	v_pk_mul_f32 v[54:55], v[54:55], v[218:219] op_sel_hi:[1,0]
	v_pk_mul_f32 v[52:53], v[52:53], v[218:219] op_sel_hi:[1,0]
	v_pk_mul_f32 v[50:51], v[50:51], v[218:219] op_sel_hi:[1,0]
	v_pk_mul_f32 v[48:49], v[48:49], v[218:219] op_sel_hi:[1,0]
	v_pk_mul_f32 v[46:47], v[46:47], v[218:219] op_sel_hi:[1,0]
	v_pk_mul_f32 v[44:45], v[44:45], v[218:219] op_sel_hi:[1,0]
	v_pk_mul_f32 v[42:43], v[42:43], v[218:219] op_sel_hi:[1,0]
	v_pk_mul_f32 v[40:41], v[40:41], v[218:219] op_sel_hi:[1,0]
	v_pk_mul_f32 v[38:39], v[38:39], v[218:219] op_sel_hi:[1,0]
	v_pk_mul_f32 v[36:37], v[36:37], v[218:219] op_sel_hi:[1,0]
	v_pk_mul_f32 v[34:35], v[34:35], v[218:219] op_sel_hi:[1,0]
	v_pk_mul_f32 v[32:33], v[32:33], v[218:219] op_sel_hi:[1,0]
	v_pk_mul_f32 v[30:31], v[30:31], v[218:219] op_sel_hi:[1,0]
	v_pk_mul_f32 v[28:29], v[28:29], v[218:219] op_sel_hi:[1,0]
	v_pk_mul_f32 v[26:27], v[26:27], v[218:219] op_sel_hi:[1,0]
	v_pk_mul_f32 v[24:25], v[24:25], v[218:219] op_sel_hi:[1,0]
	v_pk_mul_f32 v[22:23], v[22:23], v[218:219] op_sel_hi:[1,0]
	v_pk_mul_f32 v[20:21], v[20:21], v[218:219] op_sel_hi:[1,0]
	v_pk_mul_f32 v[18:19], v[18:19], v[218:219] op_sel_hi:[1,0]
	v_pk_mul_f32 v[16:17], v[16:17], v[218:219] op_sel_hi:[1,0]
	v_pk_mul_f32 v[14:15], v[14:15], v[218:219] op_sel_hi:[1,0]
	v_pk_mul_f32 v[12:13], v[12:13], v[218:219] op_sel_hi:[1,0]
	v_pk_mul_f32 v[10:11], v[10:11], v[218:219] op_sel_hi:[1,0]
	v_pk_mul_f32 v[8:9], v[8:9], v[218:219] op_sel_hi:[1,0]
	v_pk_mul_f32 v[6:7], v[6:7], v[218:219] op_sel_hi:[1,0]
	v_pk_mul_f32 v[4:5], v[4:5], v[218:219] op_sel_hi:[1,0]
	v_pk_mul_f32 v[2:3], v[2:3], v[218:219] op_sel_hi:[1,0]

.LBB0_1618:
	s_andn2_b64 vcc, exec, s[48:49]
	s_barrier
	s_waitcnt vmcnt(4)
	ds_write_b128 v229, v[146:149]
	s_waitcnt vmcnt(3)
	ds_write_b128 v230, v[150:153]
	s_waitcnt vmcnt(2)
	ds_write_b128 v231, v[154:157]
	s_waitcnt vmcnt(1)
	ds_write_b128 v232, v[162:165] offset:25600
	s_waitcnt vmcnt(0)
	ds_write_b128 v233, v[158:161] offset:25600
	s_waitcnt lgkmcnt(0)
	s_barrier
	s_cbranch_vccnz .LBB0_1597
	v_add_u32_e32 v162, v226, v225
	ds_read_b128 v[66:69], v162
	ds_read_b128 v[146:149], v162 offset:32
	ds_read_b128 v[70:73], v162 offset:12800
	ds_read_b128 v[150:153], v162 offset:12832
	s_waitcnt lgkmcnt(3)
	v_mfma_f32_32x32x16_bf16 v[82:97], v[66:69], v[142:145], 0
	ds_read_b128 v[154:157], v162 offset:64
	ds_read_b128 v[158:161], v162 offset:12864
	s_waitcnt lgkmcnt(3)
	v_mfma_f32_32x32x16_bf16 v[66:81], v[70:73], v[142:145], 0
	v_mfma_f32_32x32x16_bf16 v[82:97], v[146:149], v[138:141], v[82:97]
	ds_read_b128 v[142:145], v162 offset:96
	ds_read_b128 v[146:149], v162 offset:12896
	s_waitcnt lgkmcnt(4)
	v_mfma_f32_32x32x16_bf16 v[66:81], v[150:153], v[138:141], v[66:81]
	s_waitcnt lgkmcnt(3)
	v_mfma_f32_32x32x16_bf16 v[82:97], v[154:157], v[134:137], v[82:97]
	ds_read_b128 v[138:141], v162 offset:128
	ds_read_b128 v[150:153], v162 offset:12928
	s_waitcnt lgkmcnt(4)
	v_mfma_f32_32x32x16_bf16 v[66:81], v[158:161], v[134:137], v[66:81]
	s_waitcnt lgkmcnt(3)
	v_mfma_f32_32x32x16_bf16 v[82:97], v[142:145], v[130:133], v[82:97]
	ds_read_b128 v[134:137], v162 offset:160
	ds_read_b128 v[142:145], v162 offset:12960
	s_waitcnt lgkmcnt(4)
	v_mfma_f32_32x32x16_bf16 v[66:81], v[146:149], v[130:133], v[66:81]
	s_waitcnt lgkmcnt(3)
	v_mfma_f32_32x32x16_bf16 v[82:97], v[138:141], v[126:129], v[82:97]
	ds_read_b128 v[130:133], v162 offset:192
	ds_read_b128 v[138:141], v162 offset:12992
	s_waitcnt lgkmcnt(4)
	v_mfma_f32_32x32x16_bf16 v[66:81], v[150:153], v[126:129], v[66:81]
	s_waitcnt lgkmcnt(3)
	v_mfma_f32_32x32x16_bf16 v[82:97], v[134:137], v[122:125], v[82:97]
	ds_read_b128 v[126:129], v162 offset:224
	ds_read_b128 v[134:137], v162 offset:13024
	s_waitcnt lgkmcnt(4)
	v_mfma_f32_32x32x16_bf16 v[66:81], v[142:145], v[122:125], v[66:81]
	s_waitcnt lgkmcnt(3)
	v_mfma_f32_32x32x16_bf16 v[82:97], v[130:133], v[118:121], v[82:97]
	ds_read_b128 v[122:125], v162 offset:256
	ds_read_b128 v[130:133], v162 offset:13056
	s_waitcnt lgkmcnt(4)
	v_mfma_f32_32x32x16_bf16 v[66:81], v[138:141], v[118:121], v[66:81]
	s_waitcnt lgkmcnt(3)
	v_mfma_f32_32x32x16_bf16 v[82:97], v[126:129], v[114:117], v[82:97]
	ds_read_b128 v[118:121], v162 offset:288
	ds_read_b128 v[126:129], v162 offset:13088
	s_waitcnt lgkmcnt(4)
	v_mfma_f32_32x32x16_bf16 v[66:81], v[134:137], v[114:117], v[66:81]
	s_waitcnt lgkmcnt(3)
	v_mfma_f32_32x32x16_bf16 v[82:97], v[122:125], v[110:113], v[82:97]
	ds_read_b128 v[114:117], v162 offset:320
	ds_read_b128 v[122:125], v162 offset:13120
	s_waitcnt lgkmcnt(4)
	v_mfma_f32_32x32x16_bf16 v[66:81], v[130:133], v[110:113], v[66:81]
	s_waitcnt lgkmcnt(3)
	v_mfma_f32_32x32x16_bf16 v[82:97], v[118:121], v[106:109], v[82:97]
	ds_read_b128 v[110:113], v162 offset:352
	ds_read_b128 v[118:121], v162 offset:13152
	s_waitcnt lgkmcnt(4)
	v_mfma_f32_32x32x16_bf16 v[66:81], v[126:129], v[106:109], v[66:81]
	s_waitcnt lgkmcnt(3)
	v_mfma_f32_32x32x16_bf16 v[82:97], v[114:117], v[102:105], v[82:97]
	s_waitcnt lgkmcnt(2)
	v_mfma_f32_32x32x16_bf16 v[66:81], v[122:125], v[102:105], v[66:81]
	s_waitcnt lgkmcnt(1)
	v_mfma_f32_32x32x16_bf16 v[82:97], v[110:113], v[98:101], v[82:97]
	s_waitcnt lgkmcnt(0)
	v_mfma_f32_32x32x16_bf16 v[66:81], v[118:121], v[98:101], v[66:81]
	s_nop 9
	v_max_f32_e32 v98, v83, v83
	v_max_f32_e32 v99, v82, v82
	v_max_f32_e32 v98, v99, v98
	v_max3_f32 v98, v98, v84, v85
	v_max3_f32 v98, v98, v86, v87
	v_max3_f32 v98, v98, v88, v89
	v_max3_f32 v98, v98, v90, v91
	v_max3_f32 v98, v98, v92, v93
	v_max3_f32 v98, v98, v94, v95
	v_max3_f32 v98, v98, v96, v97
	v_max3_f32 v98, v98, v66, v67
	v_max3_f32 v98, v98, v68, v69
	v_max3_f32 v98, v98, v70, v71
	v_max3_f32 v98, v98, v72, v73
	v_max3_f32 v98, v98, v74, v75
	v_max3_f32 v98, v98, v76, v77
	v_max3_f32 v98, v98, v78, v79
	v_max3_f32 v98, v98, v80, v81
	v_mov_b32_e32 v99, v98
	s_nop 1
	v_permlane32_swap_b32_e32 v99, v98
	s_waitcnt lgkmcnt(0)
	v_max3_f32 v99, v235, v98, v99
	v_sub_f32_e32 v98, v235, v99
	v_exp_f32_e32 v98, v98
	s_nop 0
	v_cmp_neq_f32_e32 vcc, 1.0, v98
	s_cbranch_vccz .LBB0_1596
	v_pk_mul_f32 v[64:65], v[64:65], v[98:99] op_sel_hi:[1,0]
	v_pk_mul_f32 v[62:63], v[62:63], v[98:99] op_sel_hi:[1,0]
	v_pk_mul_f32 v[60:61], v[60:61], v[98:99] op_sel_hi:[1,0]
	v_pk_mul_f32 v[58:59], v[58:59], v[98:99] op_sel_hi:[1,0]
	v_pk_mul_f32 v[56:57], v[56:57], v[98:99] op_sel_hi:[1,0]
	v_pk_mul_f32 v[54:55], v[54:55], v[98:99] op_sel_hi:[1,0]
	v_pk_mul_f32 v[52:53], v[52:53], v[98:99] op_sel_hi:[1,0]
	v_pk_mul_f32 v[50:51], v[50:51], v[98:99] op_sel_hi:[1,0]
	v_pk_mul_f32 v[48:49], v[48:49], v[98:99] op_sel_hi:[1,0]
	v_pk_mul_f32 v[46:47], v[46:47], v[98:99] op_sel_hi:[1,0]
	v_pk_mul_f32 v[44:45], v[44:45], v[98:99] op_sel_hi:[1,0]
	v_pk_mul_f32 v[42:43], v[42:43], v[98:99] op_sel_hi:[1,0]
	v_pk_mul_f32 v[40:41], v[40:41], v[98:99] op_sel_hi:[1,0]
	v_pk_mul_f32 v[38:39], v[38:39], v[98:99] op_sel_hi:[1,0]
	v_pk_mul_f32 v[36:37], v[36:37], v[98:99] op_sel_hi:[1,0]
	v_pk_mul_f32 v[34:35], v[34:35], v[98:99] op_sel_hi:[1,0]
	v_pk_mul_f32 v[32:33], v[32:33], v[98:99] op_sel_hi:[1,0]
	v_pk_mul_f32 v[30:31], v[30:31], v[98:99] op_sel_hi:[1,0]
	v_pk_mul_f32 v[28:29], v[28:29], v[98:99] op_sel_hi:[1,0]
	v_pk_mul_f32 v[26:27], v[26:27], v[98:99] op_sel_hi:[1,0]
	v_pk_mul_f32 v[24:25], v[24:25], v[98:99] op_sel_hi:[1,0]
	v_pk_mul_f32 v[22:23], v[22:23], v[98:99] op_sel_hi:[1,0]
	v_pk_mul_f32 v[20:21], v[20:21], v[98:99] op_sel_hi:[1,0]
	v_pk_mul_f32 v[18:19], v[18:19], v[98:99] op_sel_hi:[1,0]
	v_pk_mul_f32 v[16:17], v[16:17], v[98:99] op_sel_hi:[1,0]
	v_pk_mul_f32 v[14:15], v[14:15], v[98:99] op_sel_hi:[1,0]
	v_pk_mul_f32 v[12:13], v[12:13], v[98:99] op_sel_hi:[1,0]
	v_pk_mul_f32 v[10:11], v[10:11], v[98:99] op_sel_hi:[1,0]
	v_pk_mul_f32 v[8:9], v[8:9], v[98:99] op_sel_hi:[1,0]
	v_pk_mul_f32 v[6:7], v[6:7], v[98:99] op_sel_hi:[1,0]
	v_pk_mul_f32 v[4:5], v[4:5], v[98:99] op_sel_hi:[1,0]
	v_pk_mul_f32 v[2:3], v[2:3], v[98:99] op_sel_hi:[1,0]
	s_branch .LBB0_1596
